# GEMM tile prologue: accumulators zeroed with 64-bit moves
# speedup vs baseline: 1.0111x; 1.0024x over previous
; template <class Epi, class Sched>
; DI void gemm_phase(LAS unsigned char* lds, const Gemm g, const Sched& S, const Epi& E) {
;     ...
;     const bool has_next = S.next(ui + 1, nxt);
;     const char* nA = has_next ? (const char*)g.A + (size_t)nxt.pm * tstep : cA; const char* nB = has_next ? (const char*)g.Bt + (size_t)nxt.pn * tstep : cB;
;     ...
; #pragma unroll
;     for (int a = 0; a < 2; ++a)
; #pragma unroll
;       for (int b = 0; b < 2; ++b)
; #pragma unroll
;         for (int m = 0; m < 4; ++m)
; #pragma unroll
;           for (int n = 0; n < 2; ++n) acc[a][b][m][n] = (f32x4){0.f, 0.f, 0.f, 0.f};
.LBB0_369:
	v_readlane_b32 s18, v239, 44
	v_readlane_b32 s19, v239, 45
	s_ashr_i32 s15, s14, 31
	s_mov_b32 s50, -2
	v_mov_b64_e32 v[0:1], s[18:19]
	v_cmp_lt_i64_e32 vcc, s[16:17], v[0:1]
	s_lshl_b64 s[16:17], s[14:15], 19
	s_add_u32 s16, s35, s16
	s_addc_u32 s17, s38, s17
	s_and_b64 s[18:19], vcc, exec
	s_cselect_b32 s15, s17, s3
	s_cselect_b32 s29, s16, s2
	s_ashr_i32 s13, s12, 31
	s_lshl_b64 s[18:19], s[12:13], 19
	s_add_u32 s18, s24, s18
	s_addc_u32 s19, s39, s19
	s_and_b64 s[20:21], vcc, exec
	s_cselect_b32 s13, s19, s5
	s_cselect_b32 s36, s18, s4
	s_add_u32 s2, s2, 0x40080
	s_addc_u32 s3, s3, 0
	s_add_u32 s37, s4, 0x100
	v_mov_b32_e32 v0, 0
	s_addc_u32 s49, s5, 0
	v_mov_b32_e32 v1, v0
	v_mov_b64_e32 v[2:3], v[0:1]
	v_mov_b64_e32 v[4:5], v[0:1]
	v_mov_b64_e32 v[6:7], v[0:1]
	v_mov_b64_e32 v[8:9], v[0:1]
	v_mov_b64_e32 v[10:11], v[0:1]
	v_mov_b64_e32 v[12:13], v[0:1]
	v_mov_b64_e32 v[14:15], v[0:1]
	v_mov_b64_e32 v[16:17], v[0:1]
	v_mov_b64_e32 v[18:19], v[0:1]
	v_mov_b64_e32 v[20:21], v[0:1]
	v_mov_b64_e32 v[22:23], v[0:1]
	v_mov_b64_e32 v[24:25], v[0:1]
	v_mov_b64_e32 v[26:27], v[0:1]
	v_mov_b64_e32 v[28:29], v[0:1]
	v_mov_b64_e32 v[30:31], v[0:1]
	v_mov_b64_e32 v[32:33], v[0:1]
	v_mov_b64_e32 v[34:35], v[0:1]
	v_mov_b64_e32 v[36:37], v[0:1]
	v_mov_b64_e32 v[38:39], v[0:1]
	v_mov_b64_e32 v[40:41], v[0:1]
	v_mov_b64_e32 v[42:43], v[0:1]
	v_mov_b64_e32 v[44:45], v[0:1]
	v_mov_b64_e32 v[46:47], v[0:1]
	v_mov_b64_e32 v[48:49], v[0:1]
	v_mov_b64_e32 v[50:51], v[0:1]
	v_mov_b64_e32 v[52:53], v[0:1]
	v_mov_b64_e32 v[54:55], v[0:1]
	v_mov_b64_e32 v[56:57], v[0:1]
	v_mov_b64_e32 v[58:59], v[0:1]
	v_mov_b64_e32 v[60:61], v[0:1]
	v_mov_b64_e32 v[62:63], v[0:1]
	v_mov_b64_e32 v[64:65], v[0:1]
	v_mov_b64_e32 v[66:67], v[0:1]
	v_mov_b64_e32 v[68:69], v[0:1]
	v_mov_b64_e32 v[70:71], v[0:1]
	v_mov_b64_e32 v[72:73], v[0:1]
	v_mov_b64_e32 v[74:75], v[0:1]
	v_mov_b64_e32 v[76:77], v[0:1]
	v_mov_b64_e32 v[78:79], v[0:1]
	v_mov_b64_e32 v[80:81], v[0:1]
	v_mov_b64_e32 v[82:83], v[0:1]
	v_mov_b64_e32 v[84:85], v[0:1]
	v_mov_b64_e32 v[86:87], v[0:1]
	v_mov_b64_e32 v[88:89], v[0:1]
	v_mov_b64_e32 v[90:91], v[0:1]
	v_mov_b64_e32 v[92:93], v[0:1]
	v_mov_b64_e32 v[94:95], v[0:1]
	v_mov_b64_e32 v[96:97], v[0:1]
	v_mov_b64_e32 v[98:99], v[0:1]
	v_mov_b64_e32 v[100:101], v[0:1]
	v_mov_b64_e32 v[102:103], v[0:1]
	v_mov_b64_e32 v[104:105], v[0:1]
	v_mov_b64_e32 v[106:107], v[0:1]
	v_mov_b64_e32 v[108:109], v[0:1]
	v_mov_b64_e32 v[110:111], v[0:1]
	v_mov_b64_e32 v[112:113], v[0:1]
	v_mov_b64_e32 v[114:115], v[0:1]
	v_mov_b64_e32 v[116:117], v[0:1]
	v_mov_b64_e32 v[118:119], v[0:1]
	v_mov_b64_e32 v[120:121], v[0:1]
	v_mov_b64_e32 v[122:123], v[0:1]
	v_mov_b64_e32 v[124:125], v[0:1]
	v_mov_b64_e32 v[126:127], v[0:1]

; template <class Epi, class Sched>
; DI void gemm_phase(LAS unsigned char* lds, const Gemm g, const Sched& S, const Epi& E) {
;     ...
;     const bool has_next = S.next(ui + 1, nxt);
;     const char* nA = has_next ? (const char*)g.A + (size_t)nxt.pm * tstep : cA; const char* nB = has_next ? (const char*)g.Bt + (size_t)nxt.pn * tstep : cB;
;     ...
; #pragma unroll
;     for (int a = 0; a < 2; ++a)
; #pragma unroll
;       for (int b = 0; b < 2; ++b)
; #pragma unroll
;         for (int m = 0; m < 4; ++m)
; #pragma unroll
;           for (int n = 0; n < 2; ++n) acc[a][b][m][n] = (f32x4){0.f, 0.f, 0.f, 0.f};
.LBB0_688:
	v_readlane_b32 s18, v238, 51
	v_readlane_b32 s19, v238, 52
	s_ashr_i32 s13, s12, 31
	s_mov_b32 s41, -2
	v_mov_b64_e32 v[0:1], s[18:19]
	v_cmp_lt_i64_e32 vcc, s[16:17], v[0:1]
	s_lshl_b64 s[16:17], s[12:13], 19
	s_add_u32 s16, s53, s16
	s_addc_u32 s17, s54, s17
	s_and_b64 s[18:19], vcc, exec
	s_cselect_b32 s13, s17, s21
	s_cselect_b32 s37, s16, s20
	s_ashr_i32 s15, s14, 31
	s_lshl_b64 s[18:19], s[14:15], 19
	s_add_u32 s18, s24, s18
	s_addc_u32 s19, s55, s19
	s_and_b64 s[28:29], vcc, exec
	s_cselect_b32 s15, s19, s23
	s_cselect_b32 s38, s18, s22
	s_add_u32 s20, s20, 0x40080
	s_addc_u32 s21, s21, 0
	s_add_u32 s39, s22, 0x100
	v_mov_b32_e32 v0, 0
	s_addc_u32 s40, s23, 0
	v_mov_b32_e32 v1, v0
	v_mov_b64_e32 v[2:3], v[0:1]
	v_mov_b64_e32 v[4:5], v[0:1]
	v_mov_b64_e32 v[6:7], v[0:1]
	v_mov_b64_e32 v[8:9], v[0:1]
	v_mov_b64_e32 v[10:11], v[0:1]
	v_mov_b64_e32 v[12:13], v[0:1]
	v_mov_b64_e32 v[14:15], v[0:1]
	v_mov_b64_e32 v[16:17], v[0:1]
	v_mov_b64_e32 v[18:19], v[0:1]
	v_mov_b64_e32 v[20:21], v[0:1]
	v_mov_b64_e32 v[22:23], v[0:1]
	v_mov_b64_e32 v[24:25], v[0:1]
	v_mov_b64_e32 v[26:27], v[0:1]
	v_mov_b64_e32 v[28:29], v[0:1]
	v_mov_b64_e32 v[30:31], v[0:1]
	v_mov_b64_e32 v[32:33], v[0:1]
	v_mov_b64_e32 v[34:35], v[0:1]
	v_mov_b64_e32 v[36:37], v[0:1]
	v_mov_b64_e32 v[38:39], v[0:1]
	v_mov_b64_e32 v[40:41], v[0:1]
	v_mov_b64_e32 v[42:43], v[0:1]
	v_mov_b64_e32 v[44:45], v[0:1]
	v_mov_b64_e32 v[46:47], v[0:1]
	v_mov_b64_e32 v[48:49], v[0:1]
	v_mov_b64_e32 v[50:51], v[0:1]
	v_mov_b64_e32 v[52:53], v[0:1]
	v_mov_b64_e32 v[54:55], v[0:1]
	v_mov_b64_e32 v[56:57], v[0:1]
	v_mov_b64_e32 v[58:59], v[0:1]
	v_mov_b64_e32 v[60:61], v[0:1]
	v_mov_b64_e32 v[62:63], v[0:1]
	v_mov_b64_e32 v[64:65], v[0:1]
	v_mov_b64_e32 v[66:67], v[0:1]
	v_mov_b64_e32 v[68:69], v[0:1]
	v_mov_b64_e32 v[70:71], v[0:1]
	v_mov_b64_e32 v[72:73], v[0:1]
	v_mov_b64_e32 v[74:75], v[0:1]
	v_mov_b64_e32 v[76:77], v[0:1]
	v_mov_b64_e32 v[78:79], v[0:1]
	v_mov_b64_e32 v[80:81], v[0:1]
	v_mov_b64_e32 v[82:83], v[0:1]
	v_mov_b64_e32 v[84:85], v[0:1]
	v_mov_b64_e32 v[86:87], v[0:1]
	v_mov_b64_e32 v[88:89], v[0:1]
	v_mov_b64_e32 v[90:91], v[0:1]
	v_mov_b64_e32 v[92:93], v[0:1]
	v_mov_b64_e32 v[94:95], v[0:1]
	v_mov_b64_e32 v[96:97], v[0:1]
	v_mov_b64_e32 v[98:99], v[0:1]
	v_mov_b64_e32 v[100:101], v[0:1]
	v_mov_b64_e32 v[102:103], v[0:1]
	v_mov_b64_e32 v[104:105], v[0:1]
	v_mov_b64_e32 v[106:107], v[0:1]
	v_mov_b64_e32 v[108:109], v[0:1]
	v_mov_b64_e32 v[110:111], v[0:1]
	v_mov_b64_e32 v[112:113], v[0:1]
	v_mov_b64_e32 v[114:115], v[0:1]
	v_mov_b64_e32 v[116:117], v[0:1]
	v_mov_b64_e32 v[118:119], v[0:1]
	v_mov_b64_e32 v[120:121], v[0:1]
	v_mov_b64_e32 v[122:123], v[0:1]
	v_mov_b64_e32 v[124:125], v[0:1]
	v_mov_b64_e32 v[126:127], v[0:1]

; template <class Epi, class Sched>
; DI void gemm_phase(LAS unsigned char* lds, const Gemm g, const Sched& S, const Epi& E) {
;     ...
; #pragma unroll
;     for (int a = 0; a < 2; ++a)
; #pragma unroll
;       for (int b = 0; b < 2; ++b)
; #pragma unroll
;         for (int m = 0; m < 4; ++m)
; #pragma unroll
;           for (int n = 0; n < 2; ++n) acc[a][b][m][n] = (f32x4){0.f, 0.f, 0.f, 0.f};
.LBB0_1201:
	s_add_u32 s52, s20, 0x100
	v_mov_b32_e32 v0, 0
	s_addc_u32 s53, s21, 0
	s_mov_b32 s54, -2
	v_mov_b32_e32 v1, v0
	v_mov_b64_e32 v[2:3], v[0:1]
	v_mov_b64_e32 v[4:5], v[0:1]
	v_mov_b64_e32 v[6:7], v[0:1]
	v_mov_b64_e32 v[8:9], v[0:1]
	v_mov_b64_e32 v[10:11], v[0:1]
	v_mov_b64_e32 v[12:13], v[0:1]
	v_mov_b64_e32 v[14:15], v[0:1]
	v_mov_b64_e32 v[16:17], v[0:1]
	v_mov_b64_e32 v[18:19], v[0:1]
	v_mov_b64_e32 v[20:21], v[0:1]
	v_mov_b64_e32 v[22:23], v[0:1]
	v_mov_b64_e32 v[24:25], v[0:1]
	v_mov_b64_e32 v[26:27], v[0:1]
	v_mov_b64_e32 v[28:29], v[0:1]
	v_mov_b64_e32 v[30:31], v[0:1]
	v_mov_b64_e32 v[32:33], v[0:1]
	v_mov_b64_e32 v[34:35], v[0:1]
	v_mov_b64_e32 v[36:37], v[0:1]
	v_mov_b64_e32 v[38:39], v[0:1]
	v_mov_b64_e32 v[40:41], v[0:1]
	v_mov_b64_e32 v[42:43], v[0:1]
	v_mov_b64_e32 v[44:45], v[0:1]
	v_mov_b64_e32 v[46:47], v[0:1]
	v_mov_b64_e32 v[48:49], v[0:1]
	v_mov_b64_e32 v[50:51], v[0:1]
	v_mov_b64_e32 v[52:53], v[0:1]
	v_mov_b64_e32 v[54:55], v[0:1]
	v_mov_b64_e32 v[56:57], v[0:1]
	v_mov_b64_e32 v[58:59], v[0:1]
	v_mov_b64_e32 v[60:61], v[0:1]
	v_mov_b64_e32 v[62:63], v[0:1]
	v_mov_b64_e32 v[64:65], v[0:1]
	v_mov_b64_e32 v[66:67], v[0:1]
	v_mov_b64_e32 v[68:69], v[0:1]
	v_mov_b64_e32 v[70:71], v[0:1]
	v_mov_b64_e32 v[72:73], v[0:1]
	v_mov_b64_e32 v[74:75], v[0:1]
	v_mov_b64_e32 v[76:77], v[0:1]
	v_mov_b64_e32 v[78:79], v[0:1]
	v_mov_b64_e32 v[80:81], v[0:1]
	v_mov_b64_e32 v[82:83], v[0:1]
	v_mov_b64_e32 v[84:85], v[0:1]
	v_mov_b64_e32 v[86:87], v[0:1]
	v_mov_b64_e32 v[88:89], v[0:1]
	v_mov_b64_e32 v[90:91], v[0:1]
	v_mov_b64_e32 v[92:93], v[0:1]
	v_mov_b64_e32 v[94:95], v[0:1]
	v_mov_b64_e32 v[96:97], v[0:1]
	v_mov_b64_e32 v[98:99], v[0:1]
	v_mov_b64_e32 v[100:101], v[0:1]
	v_mov_b64_e32 v[102:103], v[0:1]
	v_mov_b64_e32 v[104:105], v[0:1]
	v_mov_b64_e32 v[106:107], v[0:1]
	v_mov_b64_e32 v[108:109], v[0:1]
	v_mov_b64_e32 v[110:111], v[0:1]
	v_mov_b64_e32 v[112:113], v[0:1]
	v_mov_b64_e32 v[114:115], v[0:1]
	v_mov_b64_e32 v[116:117], v[0:1]
	v_mov_b64_e32 v[118:119], v[0:1]
	v_mov_b64_e32 v[120:121], v[0:1]
	v_mov_b64_e32 v[122:123], v[0:1]
	v_mov_b64_e32 v[124:125], v[0:1]
	v_mov_b64_e32 v[126:127], v[0:1]

; template <class Epi, class Sched>
; DI void gemm_phase(LAS unsigned char* lds, const Gemm g, const Sched& S, const Epi& E) {
;     ...
;     const bool has_next = S.next(ui + 1, nxt);
;     const char* nA = has_next ? (const char*)g.A + (size_t)nxt.pm * tstep : cA; const char* nB = has_next ? (const char*)g.Bt + (size_t)nxt.pn * tstep : cB;
;     ...
; #pragma unroll
;     for (int a = 0; a < 2; ++a)
; #pragma unroll
;       for (int b = 0; b < 2; ++b)
; #pragma unroll
;         for (int m = 0; m < 4; ++m)
; #pragma unroll
;           for (int n = 0; n < 2; ++n) acc[a][b][m][n] = (f32x4){0.f, 0.f, 0.f, 0.f};
.LBB0_1345:
	v_mov_b64_e32 v[0:1], s[30:31]
	s_ashr_i32 s15, s14, 31
	v_cmp_lt_i64_e32 vcc, s[16:17], v[0:1]
	s_lshl_b64 s[16:17], s[14:15], 17
	s_add_u32 s16, s52, s16
	s_addc_u32 s17, s53, s17
	s_and_b64 s[18:19], vcc, exec
	s_cselect_b32 s15, s17, s29
	s_cselect_b32 s21, s16, s28
	s_ashr_i32 s13, s12, 31
	s_lshl_b64 s[18:19], s[12:13], 17
	s_add_u32 s18, s54, s18
	s_addc_u32 s19, s55, s19
	s_and_b64 s[34:35], vcc, exec
	v_mov_b32_e32 v0, 0
	s_cselect_b32 s13, s19, s23
	s_cselect_b32 s24, s18, s22
	s_mov_b64 s[40:41], 0
	s_mov_b64 s[34:35], -1
	s_mov_b64 s[36:37], 0
	v_mov_b32_e32 v1, v0
	v_mov_b64_e32 v[2:3], v[0:1]
	v_mov_b64_e32 v[4:5], v[0:1]
	v_mov_b64_e32 v[6:7], v[0:1]
	v_mov_b64_e32 v[8:9], v[0:1]
	v_mov_b64_e32 v[10:11], v[0:1]
	v_mov_b64_e32 v[12:13], v[0:1]
	v_mov_b64_e32 v[14:15], v[0:1]
	v_mov_b64_e32 v[16:17], v[0:1]
	v_mov_b64_e32 v[18:19], v[0:1]
	v_mov_b64_e32 v[20:21], v[0:1]
	v_mov_b64_e32 v[22:23], v[0:1]
	v_mov_b64_e32 v[24:25], v[0:1]
	v_mov_b64_e32 v[26:27], v[0:1]
	v_mov_b64_e32 v[28:29], v[0:1]
	v_mov_b64_e32 v[30:31], v[0:1]
	v_mov_b64_e32 v[32:33], v[0:1]
	v_mov_b64_e32 v[34:35], v[0:1]
	v_mov_b64_e32 v[36:37], v[0:1]
	v_mov_b64_e32 v[38:39], v[0:1]
	v_mov_b64_e32 v[40:41], v[0:1]
	v_mov_b64_e32 v[42:43], v[0:1]
	v_mov_b64_e32 v[44:45], v[0:1]
	v_mov_b64_e32 v[46:47], v[0:1]
	v_mov_b64_e32 v[48:49], v[0:1]
	v_mov_b64_e32 v[50:51], v[0:1]
	v_mov_b64_e32 v[52:53], v[0:1]
	v_mov_b64_e32 v[54:55], v[0:1]
	v_mov_b64_e32 v[56:57], v[0:1]
	v_mov_b64_e32 v[58:59], v[0:1]
	v_mov_b64_e32 v[60:61], v[0:1]
	v_mov_b64_e32 v[62:63], v[0:1]
	v_mov_b64_e32 v[64:65], v[0:1]
	v_mov_b64_e32 v[66:67], v[0:1]
	v_mov_b64_e32 v[68:69], v[0:1]
	v_mov_b64_e32 v[70:71], v[0:1]
	v_mov_b64_e32 v[72:73], v[0:1]
	v_mov_b64_e32 v[74:75], v[0:1]
	v_mov_b64_e32 v[76:77], v[0:1]
	v_mov_b64_e32 v[78:79], v[0:1]
	v_mov_b64_e32 v[80:81], v[0:1]
	v_mov_b64_e32 v[82:83], v[0:1]
	v_mov_b64_e32 v[84:85], v[0:1]
	v_mov_b64_e32 v[86:87], v[0:1]
	v_mov_b64_e32 v[88:89], v[0:1]
	v_mov_b64_e32 v[90:91], v[0:1]
	v_mov_b64_e32 v[92:93], v[0:1]
	v_mov_b64_e32 v[94:95], v[0:1]
	v_mov_b64_e32 v[96:97], v[0:1]
	v_mov_b64_e32 v[98:99], v[0:1]
	v_mov_b64_e32 v[100:101], v[0:1]
	v_mov_b64_e32 v[102:103], v[0:1]
	v_mov_b64_e32 v[104:105], v[0:1]
	v_mov_b64_e32 v[106:107], v[0:1]
	v_mov_b64_e32 v[108:109], v[0:1]
	v_mov_b64_e32 v[110:111], v[0:1]
	v_mov_b64_e32 v[112:113], v[0:1]
	v_mov_b64_e32 v[114:115], v[0:1]
	v_mov_b64_e32 v[116:117], v[0:1]
	v_mov_b64_e32 v[118:119], v[0:1]
	v_mov_b64_e32 v[120:121], v[0:1]
	v_mov_b64_e32 v[122:123], v[0:1]
	v_mov_b64_e32 v[124:125], v[0:1]
	v_mov_b64_e32 v[126:127], v[0:1]

; template <class Epi, class Sched>
; DI void gemm_phase(LAS unsigned char* lds, const Gemm g, const Sched& S, const Epi& E) {
;     ...
;     const bool has_next = S.next(ui + 1, nxt);
;     const char* nA = has_next ? (const char*)g.A + (size_t)nxt.pm * tstep : cA; const char* nB = has_next ? (const char*)g.Bt + (size_t)nxt.pn * tstep : cB;
;     ...
; #pragma unroll
;     for (int a = 0; a < 2; ++a)
; #pragma unroll
;       for (int b = 0; b < 2; ++b)
; #pragma unroll
;         for (int m = 0; m < 4; ++m)
; #pragma unroll
;           for (int n = 0; n < 2; ++n) acc[a][b][m][n] = (f32x4){0.f, 0.f, 0.f, 0.f};
.LBB0_1643:
	v_mov_b64_e32 v[0:1], s[30:31]
	s_ashr_i32 s19, s18, 31
	v_cmp_lt_i64_e32 vcc, s[20:21], v[0:1]
	s_lshl_b64 s[20:21], s[18:19], 19
	s_add_u32 s20, s36, s20
	s_addc_u32 s21, s37, s21
	s_and_b64 s[22:23], vcc, exec
	s_cselect_b32 s19, s21, s3
	s_cselect_b32 s35, s20, s2
	s_ashr_i32 s17, s16, 31
	s_lshl_b64 s[22:23], s[16:17], 19
	s_add_u32 s22, s38, s22
	s_addc_u32 s23, s39, s23
	s_and_b64 s[28:29], vcc, exec
	s_cselect_b32 s17, s23, s5
	s_cselect_b32 s51, s22, s4
	s_add_u32 s2, s2, 0x40080
	s_addc_u32 s3, s3, 0
	s_add_u32 s52, s4, 0x100
	v_mov_b32_e32 v0, 0
	s_addc_u32 s53, s5, 0
	s_mov_b32 s54, -2
	v_mov_b32_e32 v1, v0
	v_mov_b64_e32 v[2:3], v[0:1]
	v_mov_b64_e32 v[4:5], v[0:1]
	v_mov_b64_e32 v[6:7], v[0:1]
	v_mov_b64_e32 v[8:9], v[0:1]
	v_mov_b64_e32 v[10:11], v[0:1]
	v_mov_b64_e32 v[12:13], v[0:1]
	v_mov_b64_e32 v[14:15], v[0:1]
	v_mov_b64_e32 v[16:17], v[0:1]
	v_mov_b64_e32 v[18:19], v[0:1]
	v_mov_b64_e32 v[20:21], v[0:1]
	v_mov_b64_e32 v[22:23], v[0:1]
	v_mov_b64_e32 v[24:25], v[0:1]
	v_mov_b64_e32 v[26:27], v[0:1]
	v_mov_b64_e32 v[28:29], v[0:1]
	v_mov_b64_e32 v[30:31], v[0:1]
	v_mov_b64_e32 v[32:33], v[0:1]
	v_mov_b64_e32 v[34:35], v[0:1]
	v_mov_b64_e32 v[36:37], v[0:1]
	v_mov_b64_e32 v[38:39], v[0:1]
	v_mov_b64_e32 v[40:41], v[0:1]
	v_mov_b64_e32 v[42:43], v[0:1]
	v_mov_b64_e32 v[44:45], v[0:1]
	v_mov_b64_e32 v[46:47], v[0:1]
	v_mov_b64_e32 v[48:49], v[0:1]
	v_mov_b64_e32 v[50:51], v[0:1]
	v_mov_b64_e32 v[52:53], v[0:1]
	v_mov_b64_e32 v[54:55], v[0:1]
	v_mov_b64_e32 v[56:57], v[0:1]
	v_mov_b64_e32 v[58:59], v[0:1]
	v_mov_b64_e32 v[60:61], v[0:1]
	v_mov_b64_e32 v[62:63], v[0:1]
	v_mov_b64_e32 v[64:65], v[0:1]
	v_mov_b64_e32 v[66:67], v[0:1]
	v_mov_b64_e32 v[68:69], v[0:1]
	v_mov_b64_e32 v[70:71], v[0:1]
	v_mov_b64_e32 v[72:73], v[0:1]
	v_mov_b64_e32 v[74:75], v[0:1]
	v_mov_b64_e32 v[76:77], v[0:1]
	v_mov_b64_e32 v[78:79], v[0:1]
	v_mov_b64_e32 v[80:81], v[0:1]
	v_mov_b64_e32 v[82:83], v[0:1]
	v_mov_b64_e32 v[84:85], v[0:1]
	v_mov_b64_e32 v[86:87], v[0:1]
	v_mov_b64_e32 v[88:89], v[0:1]
	v_mov_b64_e32 v[90:91], v[0:1]
	v_mov_b64_e32 v[92:93], v[0:1]
	v_mov_b64_e32 v[94:95], v[0:1]
	v_mov_b64_e32 v[96:97], v[0:1]
	v_mov_b64_e32 v[98:99], v[0:1]
	v_mov_b64_e32 v[100:101], v[0:1]
	v_mov_b64_e32 v[102:103], v[0:1]
	v_mov_b64_e32 v[104:105], v[0:1]
	v_mov_b64_e32 v[106:107], v[0:1]
	v_mov_b64_e32 v[108:109], v[0:1]
	v_mov_b64_e32 v[110:111], v[0:1]
	v_mov_b64_e32 v[112:113], v[0:1]
	v_mov_b64_e32 v[114:115], v[0:1]
	v_mov_b64_e32 v[116:117], v[0:1]
	v_mov_b64_e32 v[118:119], v[0:1]
	v_mov_b64_e32 v[120:121], v[0:1]
	v_mov_b64_e32 v[122:123], v[0:1]
	v_mov_b64_e32 v[124:125], v[0:1]
	v_mov_b64_e32 v[126:127], v[0:1]

; template <class Epi, class Sched>
; DI void gemm_phase(LAS unsigned char* lds, const Gemm g, const Sched& S, const Epi& E) {
;     ...
;     const bool has_next = S.next(ui + 1, nxt);
;     const char* nA = has_next ? (const char*)g.A + (size_t)nxt.pm * tstep : cA; const char* nB = has_next ? (const char*)g.Bt + (size_t)nxt.pn * tstep : cB;
;     ...
; #pragma unroll
;     for (int a = 0; a < 2; ++a)
; #pragma unroll
;       for (int b = 0; b < 2; ++b)
; #pragma unroll
;         for (int m = 0; m < 4; ++m)
; #pragma unroll
;           for (int n = 0; n < 2; ++n) acc[a][b][m][n] = (f32x4){0.f, 0.f, 0.f, 0.f};
.LBB0_1828:
	v_readlane_b32 s12, v238, 61
	v_readlane_b32 s13, v238, 62
	s_ashr_i32 s7, s6, 31
	s_mov_b32 s50, -2
	v_mov_b64_e32 v[0:1], s[12:13]
	v_cmp_lt_i64_e32 vcc, s[10:11], v[0:1]
	s_lshl_b64 s[10:11], s[6:7], 19
	s_add_u32 s10, s21, s10
	s_addc_u32 s11, s22, s11
	s_and_b64 s[12:13], vcc, exec
	s_cselect_b32 s7, s11, s15
	s_cselect_b32 s46, s10, s14
	s_ashr_i32 s5, s4, 31
	s_lshl_b64 s[12:13], s[4:5], 19
	s_add_u32 s12, s23, s12
	s_addc_u32 s13, s28, s13
	s_and_b64 s[18:19], vcc, exec
	s_cselect_b32 s5, s13, s17
	s_cselect_b32 s47, s12, s16
	s_add_u32 s14, s14, 0x40080
	s_addc_u32 s15, s15, 0
	s_add_u32 s48, s16, 0x100
	v_mov_b32_e32 v0, 0
	s_addc_u32 s49, s17, 0
	v_mov_b32_e32 v1, v0
	v_mov_b64_e32 v[2:3], v[0:1]
	v_mov_b64_e32 v[4:5], v[0:1]
	v_mov_b64_e32 v[6:7], v[0:1]
	v_mov_b64_e32 v[8:9], v[0:1]
	v_mov_b64_e32 v[10:11], v[0:1]
	v_mov_b64_e32 v[12:13], v[0:1]
	v_mov_b64_e32 v[14:15], v[0:1]
	v_mov_b64_e32 v[16:17], v[0:1]
	v_mov_b64_e32 v[18:19], v[0:1]
	v_mov_b64_e32 v[20:21], v[0:1]
	v_mov_b64_e32 v[22:23], v[0:1]
	v_mov_b64_e32 v[24:25], v[0:1]
	v_mov_b64_e32 v[26:27], v[0:1]
	v_mov_b64_e32 v[28:29], v[0:1]
	v_mov_b64_e32 v[30:31], v[0:1]
	v_mov_b64_e32 v[32:33], v[0:1]
	v_mov_b64_e32 v[34:35], v[0:1]
	v_mov_b64_e32 v[36:37], v[0:1]
	v_mov_b64_e32 v[38:39], v[0:1]
	v_mov_b64_e32 v[40:41], v[0:1]
	v_mov_b64_e32 v[42:43], v[0:1]
	v_mov_b64_e32 v[44:45], v[0:1]
	v_mov_b64_e32 v[46:47], v[0:1]
	v_mov_b64_e32 v[48:49], v[0:1]
	v_mov_b64_e32 v[50:51], v[0:1]
	v_mov_b64_e32 v[52:53], v[0:1]
	v_mov_b64_e32 v[54:55], v[0:1]
	v_mov_b64_e32 v[56:57], v[0:1]
	v_mov_b64_e32 v[58:59], v[0:1]
	v_mov_b64_e32 v[60:61], v[0:1]
	v_mov_b64_e32 v[62:63], v[0:1]
	v_mov_b64_e32 v[64:65], v[0:1]
	v_mov_b64_e32 v[66:67], v[0:1]
	v_mov_b64_e32 v[68:69], v[0:1]
	v_mov_b64_e32 v[70:71], v[0:1]
	v_mov_b64_e32 v[72:73], v[0:1]
	v_mov_b64_e32 v[74:75], v[0:1]
	v_mov_b64_e32 v[76:77], v[0:1]
	v_mov_b64_e32 v[78:79], v[0:1]
	v_mov_b64_e32 v[80:81], v[0:1]
	v_mov_b64_e32 v[82:83], v[0:1]
	v_mov_b64_e32 v[84:85], v[0:1]
	v_mov_b64_e32 v[86:87], v[0:1]
	v_mov_b64_e32 v[88:89], v[0:1]
	v_mov_b64_e32 v[90:91], v[0:1]
	v_mov_b64_e32 v[92:93], v[0:1]
	v_mov_b64_e32 v[94:95], v[0:1]
	v_mov_b64_e32 v[96:97], v[0:1]
	v_mov_b64_e32 v[98:99], v[0:1]
	v_mov_b64_e32 v[100:101], v[0:1]
	v_mov_b64_e32 v[102:103], v[0:1]
	v_mov_b64_e32 v[104:105], v[0:1]
	v_mov_b64_e32 v[106:107], v[0:1]
	v_mov_b64_e32 v[108:109], v[0:1]
	v_mov_b64_e32 v[110:111], v[0:1]
	v_mov_b64_e32 v[112:113], v[0:1]
	v_mov_b64_e32 v[114:115], v[0:1]
	v_mov_b64_e32 v[116:117], v[0:1]
	v_mov_b64_e32 v[118:119], v[0:1]
	v_mov_b64_e32 v[120:121], v[0:1]
	v_mov_b64_e32 v[122:123], v[0:1]
	v_mov_b64_e32 v[124:125], v[0:1]
	v_mov_b64_e32 v[126:127], v[0:1]

; template <class Epi, class Sched>
; DI void gemm_phase(LAS unsigned char* lds, const Gemm g, const Sched& S, const Epi& E) {
;     ...
;     const bool has_next = S.next(ui + 1, nxt);
;     const char* nA = has_next ? (const char*)g.A + (size_t)nxt.pm * tstep : cA; const char* nB = has_next ? (const char*)g.Bt + (size_t)nxt.pn * tstep : cB;
;     ...
; #pragma unroll
;     for (int a = 0; a < 2; ++a)
; #pragma unroll
;       for (int b = 0; b < 2; ++b)
; #pragma unroll
;         for (int m = 0; m < 4; ++m)
; #pragma unroll
;           for (int n = 0; n < 2; ++n) acc[a][b][m][n] = (f32x4){0.f, 0.f, 0.f, 0.f};
.LBB0_1904:
	v_mov_b64_e32 v[0:1], s[30:31]
	s_ashr_i32 s11, s10, 31
	v_cmp_lt_i64_e32 vcc, s[12:13], v[0:1]
	s_lshl_b64 s[12:13], s[10:11], 21
	s_add_u32 s12, s34, s12
	s_addc_u32 s13, s35, s13
	s_and_b64 s[14:15], vcc, exec
	s_cselect_b32 s11, s13, s21
	s_cselect_b32 s17, s12, s20
	s_ashr_i32 s7, s6, 31
	s_lshl_b64 s[14:15], s[6:7], 21
	s_add_u32 s14, s36, s14
	s_addc_u32 s15, s37, s15
	s_and_b64 s[28:29], vcc, exec
	s_cselect_b32 s7, s15, s23
	s_cselect_b32 s19, s14, s22
	s_add_u32 s20, s20, 0x100080
	s_addc_u32 s21, s21, 0
	s_add_u32 s24, s22, 0x100
	v_mov_b32_e32 v0, 0
	s_addc_u32 s49, s23, 0
	s_mov_b32 s50, -2
	v_mov_b32_e32 v1, v0
	v_mov_b64_e32 v[2:3], v[0:1]
	v_mov_b64_e32 v[4:5], v[0:1]
	v_mov_b64_e32 v[6:7], v[0:1]
	v_mov_b64_e32 v[8:9], v[0:1]
	v_mov_b64_e32 v[10:11], v[0:1]
	v_mov_b64_e32 v[12:13], v[0:1]
	v_mov_b64_e32 v[14:15], v[0:1]
	v_mov_b64_e32 v[16:17], v[0:1]
	v_mov_b64_e32 v[18:19], v[0:1]
	v_mov_b64_e32 v[20:21], v[0:1]
	v_mov_b64_e32 v[22:23], v[0:1]
	v_mov_b64_e32 v[24:25], v[0:1]
	v_mov_b64_e32 v[26:27], v[0:1]
	v_mov_b64_e32 v[28:29], v[0:1]
	v_mov_b64_e32 v[30:31], v[0:1]
	v_mov_b64_e32 v[32:33], v[0:1]
	v_mov_b64_e32 v[34:35], v[0:1]
	v_mov_b64_e32 v[36:37], v[0:1]
	v_mov_b64_e32 v[38:39], v[0:1]
	v_mov_b64_e32 v[40:41], v[0:1]
	v_mov_b64_e32 v[42:43], v[0:1]
	v_mov_b64_e32 v[44:45], v[0:1]
	v_mov_b64_e32 v[46:47], v[0:1]
	v_mov_b64_e32 v[48:49], v[0:1]
	v_mov_b64_e32 v[50:51], v[0:1]
	v_mov_b64_e32 v[52:53], v[0:1]
	v_mov_b64_e32 v[54:55], v[0:1]
	v_mov_b64_e32 v[56:57], v[0:1]
	v_mov_b64_e32 v[58:59], v[0:1]
	v_mov_b64_e32 v[60:61], v[0:1]
	v_mov_b64_e32 v[62:63], v[0:1]
	v_mov_b64_e32 v[64:65], v[0:1]
	v_mov_b64_e32 v[66:67], v[0:1]
	v_mov_b64_e32 v[68:69], v[0:1]
	v_mov_b64_e32 v[70:71], v[0:1]
	v_mov_b64_e32 v[72:73], v[0:1]
	v_mov_b64_e32 v[74:75], v[0:1]
	v_mov_b64_e32 v[76:77], v[0:1]
	v_mov_b64_e32 v[78:79], v[0:1]
	v_mov_b64_e32 v[80:81], v[0:1]
	v_mov_b64_e32 v[82:83], v[0:1]
	v_mov_b64_e32 v[84:85], v[0:1]
	v_mov_b64_e32 v[86:87], v[0:1]
	v_mov_b64_e32 v[88:89], v[0:1]
	v_mov_b64_e32 v[90:91], v[0:1]
	v_mov_b64_e32 v[92:93], v[0:1]
	v_mov_b64_e32 v[94:95], v[0:1]
	v_mov_b64_e32 v[96:97], v[0:1]
	v_mov_b64_e32 v[98:99], v[0:1]
	v_mov_b64_e32 v[100:101], v[0:1]
	v_mov_b64_e32 v[102:103], v[0:1]
	v_mov_b64_e32 v[104:105], v[0:1]
	v_mov_b64_e32 v[106:107], v[0:1]
	v_mov_b64_e32 v[108:109], v[0:1]
	v_mov_b64_e32 v[110:111], v[0:1]
	v_mov_b64_e32 v[112:113], v[0:1]
	v_mov_b64_e32 v[114:115], v[0:1]
	v_mov_b64_e32 v[116:117], v[0:1]
	v_mov_b64_e32 v[118:119], v[0:1]
	v_mov_b64_e32 v[120:121], v[0:1]
	v_mov_b64_e32 v[122:123], v[0:1]
	v_mov_b64_e32 v[124:125], v[0:1]
	v_mov_b64_e32 v[126:127], v[0:1]
